# v063 with R=2: GEMV blocks also convert 2 layer-0 tiles each in P0
# speedup vs baseline: 1.0009x; 1.0009x over previous
.LBB0_17:
	s_mov_b32 s94, 0
	s_mov_b32 s95, 0
	s_movk_i32 s96, 0x2c0
	s_movk_i32 s97, 0x420
	s_movk_i32 s93, 0x500
	s_sub_i32 s92, 0xff, s2
	s_mov_b32 s90, s42

.LBB0_20:
	v_lshlrev_b32_e32 v2, 5, v5
	v_and_b32_e32 v5, 0x60, v2
	v_ashrrev_i32_e32 v2, 31, v7
	v_mul_lo_u32 v10, s25, v7
	v_mul_lo_u32 v2, s24, v2
	v_mad_u64_u32 v[8:9], s[24:25], s24, v7, 0
	v_add3_u32 v9, v9, v2, v10
	v_lshlrev_b32_e32 v2, 1, v5
	v_lshlrev_b32_e32 v6, 2, v6
	v_mul_u32_u24_e32 v5, 0x204, v5
	v_lshl_add_u64 v[8:9], v[8:9], 1, s[22:23]
	s_ashr_i32 s29, s28, 31
	v_add3_u32 v5, 0, v6, v5
	v_lshl_add_u64 v[8:9], s[28:29], 1, v[8:9]
	v_add_u32_e32 v10, 0x400, v5
	ds_read2_b32 v[6:7], v5 offset1:129
	ds_read2_b32 v[10:11], v10 offset0:2 offset1:131
	v_add_u32_e32 v12, 0x800, v5
	v_add_u32_e32 v14, 0xc00, v5
	v_lshl_add_u64 v[16:17], v[8:9], 0, v[2:3]
	v_add_u32_e32 v2, 0x1000, v5
	ds_read2_b32 v[12:13], v12 offset0:4 offset1:133
	ds_read2_b32 v[14:15], v14 offset0:6 offset1:135
	s_waitcnt lgkmcnt(3)
	v_cvt_pk_bf16_f32 v6, v6, v7
	s_waitcnt lgkmcnt(2)
	v_cvt_pk_bf16_f32 v7, v10, v11
	s_waitcnt lgkmcnt(1)
	v_cvt_pk_bf16_f32 v8, v12, v13
	s_waitcnt lgkmcnt(0)
	v_cvt_pk_bf16_f32 v9, v14, v15
	ds_read2_b32 v[10:11], v2 offset0:8 offset1:137
	v_add_u32_e32 v2, 0x1400, v5
	ds_read2_b32 v[12:13], v2 offset0:10 offset1:139
	v_add_u32_e32 v2, 0x1800, v5
	ds_read2_b32 v[14:15], v2 offset0:12 offset1:141
	v_add_u32_e32 v2, 0x1c00, v5
	ds_read2_b32 v[18:19], v2 offset0:14 offset1:143
	v_add_u32_e32 v2, 0x2000, v5
	global_store_dwordx4 v[16:17], v[6:9], off
	s_waitcnt lgkmcnt(3)
	v_cvt_pk_bf16_f32 v6, v10, v11
	s_waitcnt lgkmcnt(2)
	v_cvt_pk_bf16_f32 v7, v12, v13
	s_waitcnt lgkmcnt(1)
	v_cvt_pk_bf16_f32 v8, v14, v15
	s_waitcnt lgkmcnt(0)
	v_cvt_pk_bf16_f32 v9, v18, v19
	ds_read2_b32 v[10:11], v2 offset0:16 offset1:145
	v_add_u32_e32 v2, 0x2400, v5
	ds_read2_b32 v[12:13], v2 offset0:18 offset1:147
	v_add_u32_e32 v2, 0x2800, v5
	ds_read2_b32 v[14:15], v2 offset0:20 offset1:149
	v_add_u32_e32 v2, 0x2c00, v5
	ds_read2_b32 v[18:19], v2 offset0:22 offset1:151
	v_add_u32_e32 v2, 0x3000, v5
	global_store_dwordx4 v[16:17], v[6:9], off offset:16
	s_waitcnt lgkmcnt(3)
	s_nop 0
	v_cvt_pk_bf16_f32 v6, v10, v11
	s_waitcnt lgkmcnt(2)
	v_cvt_pk_bf16_f32 v7, v12, v13
	s_waitcnt lgkmcnt(1)
	v_cvt_pk_bf16_f32 v8, v14, v15
	s_waitcnt lgkmcnt(0)
	v_cvt_pk_bf16_f32 v9, v18, v19
	ds_read2_b32 v[10:11], v2 offset0:24 offset1:153
	v_add_u32_e32 v2, 0x3400, v5
	ds_read2_b32 v[12:13], v2 offset0:26 offset1:155
	v_add_u32_e32 v2, 0x3800, v5
	ds_read2_b32 v[14:15], v2 offset0:28 offset1:157
	v_add_u32_e32 v2, 0x3c00, v5
	ds_read2_b32 v[18:19], v2 offset0:30 offset1:159
	global_store_dwordx4 v[16:17], v[6:9], off offset:32
	s_waitcnt lgkmcnt(3)
	s_nop 0
	v_cvt_pk_bf16_f32 v6, v10, v11
	s_waitcnt lgkmcnt(2)
	v_cvt_pk_bf16_f32 v7, v12, v13
	s_waitcnt lgkmcnt(1)
	v_cvt_pk_bf16_f32 v8, v14, v15
	s_waitcnt lgkmcnt(0)
	v_cvt_pk_bf16_f32 v9, v18, v19
	global_store_dwordx4 v[16:17], v[6:9], off offset:48
	s_barrier
	s_add_i32 s92, s92, s90
	s_cmp_lg_u32 s90, s42
	s_cbranch_scc1 .Lmy_cv_nomap
	s_cmp_lg_u32 s94, 0
	s_cbranch_scc1 .Lmy_cv_nomap
	s_cmpk_lt_i32 s92, 512
	s_cbranch_scc1 .Lmy_cv_nomap
	s_sub_i32 s91, s92, 512
	s_cmpk_gt_i32 s91, 111
	s_cselect_b32 s92, 0x7fff, s92
	s_movk_i32 s90, 112
.Lmy_cv_nomap:
	s_cmp_lt_i32 s92, s93
	s_cbranch_scc1 .Lmy_cv_head
	s_cmp_eq_u32 s94, 0
	s_cbranch_scc1 .LBB0_52
	s_cmp_eq_u32 s94, 1
	s_cbranch_scc1 .Lmy_cv_ret1
	s_cmp_eq_u32 s94, 2
	s_cbranch_scc1 .Lmy_cv_ret2
	s_branch .Lmy_cv_ret3
